# fused epilogue: half of the residual tile (four 4-row groups) staged row-contiguous into the idle GEMM stage buffers by LDS-DMA before the row-sum exchange, all waves prefetch before the exchange
# baseline (speedup 1.0000x reference)
.Lgo_fz_epi:
	s_nop 7
	s_nop 7
	s_load_dwordx2 s[94:95], s[88:89], 0x168
	s_load_dwordx2 s[98:99], s[88:89], 0x170
	s_load_dwordx2 s[2:3], s[88:89], 0xc0
	v_and_b32_e32 v160, 15, v167
	v_bfe_u32 v161, v167, 4, 2
	v_bfe_u32 v162, v167, 6, 2
	v_lshrrev_b32_e32 v163, 8, v167
	v_lshlrev_b32_e32 v163, 6, v163
	v_lshl_add_u32 v163, v161, 2, v163
	v_lshl_add_u32 v164, v162, 5, v160
	v_readlane_b32 s32, v255, 0
	s_lshr_b32 s45, s36, 8
	s_lshl_b32 s48, s45, 3
	s_lshr_b32 s57, s34, 8
	s_add_u32 s48, s48, s57
	s_lshl_b32 s48, s48, 10
	s_lshr_b32 s57, s36, 12
	s_mul_i32 s0, s32, 5
	s_add_u32 s57, s57, s0
	s_mul_i32 s57, s57, 0x6000
	s_add_u32 s57, s57, 0x4000
	v_lshlrev_b32_e32 v237, 2, v164
	s_lshl_b32 vcc_lo, s34, 2
	v_add_u32_e32 v237, vcc_lo, v237
	v_add_u32_e32 v168, s36, v163
	v_lshlrev_b32_e32 v168, 13, v168
	v_add_u32_e32 v168, v168, v237
	v_add_u32_e32 v169, 0x2000, v168
	v_add_u32_e32 v170, 0x4000, v168
	v_add_u32_e32 v171, 0x6000, v168
	v_and_b32_e32 v182, 63, v167
	v_lshlrev_b32_e32 v182, 4, v182
	s_lshl_b32 vcc_lo, s36, 13
	v_add_u32_e32 v182, vcc_lo, v182
	s_lshl_b32 vcc_lo, s34, 2
	v_add_u32_e32 v182, vcc_lo, v182
	v_lshrrev_b32_e32 v183, 8, v167
	v_lshlrev_b32_e32 v183, 14, v183
	v_lshl_add_u32 v183, v161, 12, v183
	v_lshl_add_u32 v161, v164, 2, v183
	s_lshl_b32 s0, s45, 2
	s_add_u32 s0, s0, 0x204
	v_mov_b32_e32 v234, s0
	s_lshl_b32 s0, s45, 13
	v_lshl_add_u32 v235, v167, 2, s0
	s_lshl_b32 s45, s32, 3
	s_add_u32 s45, s45, 8
	s_load_dwordx2 s[36:37], s[88:89], 0xc8
	s_load_dwordx2 s[34:35], s[88:89], 0xf0
	s_load_dwordx2 s[0:1], s[88:89], 0x0
	v_mul_f32_e32 v194, v124, v124
	v_fmac_f32_e32 v194, v120, v120
	v_fmac_f32_e32 v194, v100, v100
	v_fmac_f32_e32 v194, v96, v96
	v_mul_f32_e32 v195, v125, v125
	v_fmac_f32_e32 v195, v121, v121
	v_fmac_f32_e32 v195, v101, v101
	v_fmac_f32_e32 v195, v97, v97
	v_mul_f32_e32 v196, v126, v126
	v_fmac_f32_e32 v196, v122, v122
	v_fmac_f32_e32 v196, v102, v102
	v_fmac_f32_e32 v196, v98, v98
	v_mul_f32_e32 v197, v127, v127
	v_fmac_f32_e32 v197, v123, v123
	v_fmac_f32_e32 v197, v103, v103
	v_fmac_f32_e32 v197, v99, v99
	v_mul_f32_e32 v198, v116, v116
	v_fmac_f32_e32 v198, v112, v112
	v_fmac_f32_e32 v198, v92, v92
	v_fmac_f32_e32 v198, v88, v88
	v_mul_f32_e32 v199, v117, v117
	v_fmac_f32_e32 v199, v113, v113
	v_fmac_f32_e32 v199, v93, v93
	v_fmac_f32_e32 v199, v89, v89
	v_mul_f32_e32 v200, v118, v118
	v_fmac_f32_e32 v200, v114, v114
	v_fmac_f32_e32 v200, v94, v94
	v_fmac_f32_e32 v200, v90, v90
	v_mul_f32_e32 v201, v119, v119
	v_fmac_f32_e32 v201, v115, v115
	v_fmac_f32_e32 v201, v95, v95
	v_fmac_f32_e32 v201, v91, v91
	v_mul_f32_e32 v202, v108, v108
	v_fmac_f32_e32 v202, v104, v104
	v_fmac_f32_e32 v202, v80, v80
	v_fmac_f32_e32 v202, v72, v72
	v_mul_f32_e32 v203, v109, v109
	v_fmac_f32_e32 v203, v105, v105
	v_fmac_f32_e32 v203, v81, v81
	v_fmac_f32_e32 v203, v73, v73
	v_mul_f32_e32 v204, v110, v110
	v_fmac_f32_e32 v204, v106, v106
	v_fmac_f32_e32 v204, v82, v82
	v_fmac_f32_e32 v204, v74, v74
	v_mul_f32_e32 v205, v111, v111
	v_fmac_f32_e32 v205, v107, v107
	v_fmac_f32_e32 v205, v83, v83
	v_fmac_f32_e32 v205, v75, v75
	v_mul_f32_e32 v206, v84, v84
	v_fmac_f32_e32 v206, v76, v76
	v_fmac_f32_e32 v206, v68, v68
	v_fmac_f32_e32 v206, v64, v64
	v_mul_f32_e32 v207, v85, v85
	v_fmac_f32_e32 v207, v77, v77
	v_fmac_f32_e32 v207, v69, v69
	v_fmac_f32_e32 v207, v65, v65
	v_mul_f32_e32 v208, v86, v86
	v_fmac_f32_e32 v208, v78, v78
	v_fmac_f32_e32 v208, v70, v70
	v_fmac_f32_e32 v208, v66, v66
	v_mul_f32_e32 v209, v87, v87
	v_fmac_f32_e32 v209, v79, v79
	v_fmac_f32_e32 v209, v71, v71
	v_fmac_f32_e32 v209, v67, v67
	v_mul_f32_e32 v210, v60, v60
	v_fmac_f32_e32 v210, v56, v56
	v_fmac_f32_e32 v210, v32, v32
	v_fmac_f32_e32 v210, v24, v24
	v_mul_f32_e32 v211, v61, v61
	v_fmac_f32_e32 v211, v57, v57
	v_fmac_f32_e32 v211, v33, v33
	v_fmac_f32_e32 v211, v25, v25
	v_mul_f32_e32 v212, v62, v62
	v_fmac_f32_e32 v212, v58, v58
	v_fmac_f32_e32 v212, v34, v34
	v_fmac_f32_e32 v212, v26, v26
	v_mul_f32_e32 v213, v63, v63
	v_fmac_f32_e32 v213, v59, v59
	v_fmac_f32_e32 v213, v35, v35
	v_fmac_f32_e32 v213, v27, v27
	v_mul_f32_e32 v214, v52, v52
	v_fmac_f32_e32 v214, v48, v48
	v_fmac_f32_e32 v214, v20, v20
	v_fmac_f32_e32 v214, v16, v16
	v_mul_f32_e32 v215, v53, v53
	v_fmac_f32_e32 v215, v49, v49
	v_fmac_f32_e32 v215, v21, v21
	v_fmac_f32_e32 v215, v17, v17
	v_mul_f32_e32 v216, v54, v54
	v_fmac_f32_e32 v216, v50, v50
	v_fmac_f32_e32 v216, v22, v22
	v_fmac_f32_e32 v216, v18, v18
	v_mul_f32_e32 v217, v55, v55
	v_fmac_f32_e32 v217, v51, v51
	v_fmac_f32_e32 v217, v23, v23
	v_fmac_f32_e32 v217, v19, v19
	v_mul_f32_e32 v218, v44, v44
	v_fmac_f32_e32 v218, v40, v40
	v_fmac_f32_e32 v218, v12, v12
	v_fmac_f32_e32 v218, v8, v8
	v_mul_f32_e32 v219, v45, v45
	v_fmac_f32_e32 v219, v41, v41
	v_fmac_f32_e32 v219, v13, v13
	v_fmac_f32_e32 v219, v9, v9
	v_mul_f32_e32 v220, v46, v46
	v_fmac_f32_e32 v220, v42, v42
	v_fmac_f32_e32 v220, v14, v14
	v_fmac_f32_e32 v220, v10, v10
	v_mul_f32_e32 v221, v47, v47
	v_fmac_f32_e32 v221, v43, v43
	v_fmac_f32_e32 v221, v15, v15
	v_fmac_f32_e32 v221, v11, v11
	v_mul_f32_e32 v222, v36, v36
	v_fmac_f32_e32 v222, v28, v28
	v_fmac_f32_e32 v222, v4, v4
	v_fmac_f32_e32 v222, v0, v0
	v_mul_f32_e32 v223, v37, v37
	v_fmac_f32_e32 v223, v29, v29
	v_fmac_f32_e32 v223, v5, v5
	v_fmac_f32_e32 v223, v1, v1
	v_mul_f32_e32 v224, v38, v38
	v_fmac_f32_e32 v224, v30, v30
	v_fmac_f32_e32 v224, v6, v6
	v_fmac_f32_e32 v224, v2, v2
	v_mul_f32_e32 v225, v39, v39
	v_fmac_f32_e32 v225, v31, v31
	v_fmac_f32_e32 v225, v7, v7
	v_fmac_f32_e32 v225, v3, v3
	s_nop 1
	v_add_f32_dpp v194, v194, v194 row_ror:8 row_mask:0xf bank_mask:0xf
	v_add_f32_dpp v195, v195, v195 row_ror:8 row_mask:0xf bank_mask:0xf
	v_add_f32_dpp v196, v196, v196 row_ror:8 row_mask:0xf bank_mask:0xf
	v_add_f32_dpp v197, v197, v197 row_ror:8 row_mask:0xf bank_mask:0xf
	v_add_f32_dpp v198, v198, v198 row_ror:8 row_mask:0xf bank_mask:0xf
	v_add_f32_dpp v199, v199, v199 row_ror:8 row_mask:0xf bank_mask:0xf
	v_add_f32_dpp v200, v200, v200 row_ror:8 row_mask:0xf bank_mask:0xf
	v_add_f32_dpp v201, v201, v201 row_ror:8 row_mask:0xf bank_mask:0xf
	v_add_f32_dpp v202, v202, v202 row_ror:8 row_mask:0xf bank_mask:0xf
	v_add_f32_dpp v203, v203, v203 row_ror:8 row_mask:0xf bank_mask:0xf
	v_add_f32_dpp v204, v204, v204 row_ror:8 row_mask:0xf bank_mask:0xf
	v_add_f32_dpp v205, v205, v205 row_ror:8 row_mask:0xf bank_mask:0xf
	v_add_f32_dpp v206, v206, v206 row_ror:8 row_mask:0xf bank_mask:0xf
	v_add_f32_dpp v207, v207, v207 row_ror:8 row_mask:0xf bank_mask:0xf
	v_add_f32_dpp v208, v208, v208 row_ror:8 row_mask:0xf bank_mask:0xf
	v_add_f32_dpp v209, v209, v209 row_ror:8 row_mask:0xf bank_mask:0xf
	v_add_f32_dpp v210, v210, v210 row_ror:8 row_mask:0xf bank_mask:0xf
	v_add_f32_dpp v211, v211, v211 row_ror:8 row_mask:0xf bank_mask:0xf
	v_add_f32_dpp v212, v212, v212 row_ror:8 row_mask:0xf bank_mask:0xf
	v_add_f32_dpp v213, v213, v213 row_ror:8 row_mask:0xf bank_mask:0xf
	v_add_f32_dpp v214, v214, v214 row_ror:8 row_mask:0xf bank_mask:0xf
	v_add_f32_dpp v215, v215, v215 row_ror:8 row_mask:0xf bank_mask:0xf
	v_add_f32_dpp v216, v216, v216 row_ror:8 row_mask:0xf bank_mask:0xf
	v_add_f32_dpp v217, v217, v217 row_ror:8 row_mask:0xf bank_mask:0xf
	v_add_f32_dpp v218, v218, v218 row_ror:8 row_mask:0xf bank_mask:0xf
	v_add_f32_dpp v219, v219, v219 row_ror:8 row_mask:0xf bank_mask:0xf
	v_add_f32_dpp v220, v220, v220 row_ror:8 row_mask:0xf bank_mask:0xf
	v_add_f32_dpp v221, v221, v221 row_ror:8 row_mask:0xf bank_mask:0xf
	v_add_f32_dpp v222, v222, v222 row_ror:8 row_mask:0xf bank_mask:0xf
	v_add_f32_dpp v223, v223, v223 row_ror:8 row_mask:0xf bank_mask:0xf
	v_add_f32_dpp v224, v224, v224 row_ror:8 row_mask:0xf bank_mask:0xf
	v_add_f32_dpp v225, v225, v225 row_ror:8 row_mask:0xf bank_mask:0xf
	s_nop 1
	v_add_f32_dpp v194, v194, v194 row_ror:4 row_mask:0xf bank_mask:0xf
	v_add_f32_dpp v195, v195, v195 row_ror:4 row_mask:0xf bank_mask:0xf
	v_add_f32_dpp v196, v196, v196 row_ror:4 row_mask:0xf bank_mask:0xf
	v_add_f32_dpp v197, v197, v197 row_ror:4 row_mask:0xf bank_mask:0xf
	v_add_f32_dpp v198, v198, v198 row_ror:4 row_mask:0xf bank_mask:0xf
	v_add_f32_dpp v199, v199, v199 row_ror:4 row_mask:0xf bank_mask:0xf
	v_add_f32_dpp v200, v200, v200 row_ror:4 row_mask:0xf bank_mask:0xf
	v_add_f32_dpp v201, v201, v201 row_ror:4 row_mask:0xf bank_mask:0xf
	v_add_f32_dpp v202, v202, v202 row_ror:4 row_mask:0xf bank_mask:0xf
	v_add_f32_dpp v203, v203, v203 row_ror:4 row_mask:0xf bank_mask:0xf
	v_add_f32_dpp v204, v204, v204 row_ror:4 row_mask:0xf bank_mask:0xf
	v_add_f32_dpp v205, v205, v205 row_ror:4 row_mask:0xf bank_mask:0xf
	v_add_f32_dpp v206, v206, v206 row_ror:4 row_mask:0xf bank_mask:0xf
	v_add_f32_dpp v207, v207, v207 row_ror:4 row_mask:0xf bank_mask:0xf
	v_add_f32_dpp v208, v208, v208 row_ror:4 row_mask:0xf bank_mask:0xf
	v_add_f32_dpp v209, v209, v209 row_ror:4 row_mask:0xf bank_mask:0xf
	v_add_f32_dpp v210, v210, v210 row_ror:4 row_mask:0xf bank_mask:0xf
	v_add_f32_dpp v211, v211, v211 row_ror:4 row_mask:0xf bank_mask:0xf
	v_add_f32_dpp v212, v212, v212 row_ror:4 row_mask:0xf bank_mask:0xf
	v_add_f32_dpp v213, v213, v213 row_ror:4 row_mask:0xf bank_mask:0xf
	v_add_f32_dpp v214, v214, v214 row_ror:4 row_mask:0xf bank_mask:0xf
	v_add_f32_dpp v215, v215, v215 row_ror:4 row_mask:0xf bank_mask:0xf
	v_add_f32_dpp v216, v216, v216 row_ror:4 row_mask:0xf bank_mask:0xf
	v_add_f32_dpp v217, v217, v217 row_ror:4 row_mask:0xf bank_mask:0xf
	v_add_f32_dpp v218, v218, v218 row_ror:4 row_mask:0xf bank_mask:0xf
	v_add_f32_dpp v219, v219, v219 row_ror:4 row_mask:0xf bank_mask:0xf
	v_add_f32_dpp v220, v220, v220 row_ror:4 row_mask:0xf bank_mask:0xf
	v_add_f32_dpp v221, v221, v221 row_ror:4 row_mask:0xf bank_mask:0xf
	v_add_f32_dpp v222, v222, v222 row_ror:4 row_mask:0xf bank_mask:0xf
	v_add_f32_dpp v223, v223, v223 row_ror:4 row_mask:0xf bank_mask:0xf
	v_add_f32_dpp v224, v224, v224 row_ror:4 row_mask:0xf bank_mask:0xf
	v_add_f32_dpp v225, v225, v225 row_ror:4 row_mask:0xf bank_mask:0xf
	s_nop 1
	v_add_f32_dpp v194, v194, v194 row_ror:2 row_mask:0xf bank_mask:0xf
	v_add_f32_dpp v195, v195, v195 row_ror:2 row_mask:0xf bank_mask:0xf
	v_add_f32_dpp v196, v196, v196 row_ror:2 row_mask:0xf bank_mask:0xf
	v_add_f32_dpp v197, v197, v197 row_ror:2 row_mask:0xf bank_mask:0xf
	v_add_f32_dpp v198, v198, v198 row_ror:2 row_mask:0xf bank_mask:0xf
	v_add_f32_dpp v199, v199, v199 row_ror:2 row_mask:0xf bank_mask:0xf
	v_add_f32_dpp v200, v200, v200 row_ror:2 row_mask:0xf bank_mask:0xf
	v_add_f32_dpp v201, v201, v201 row_ror:2 row_mask:0xf bank_mask:0xf
	v_add_f32_dpp v202, v202, v202 row_ror:2 row_mask:0xf bank_mask:0xf
	v_add_f32_dpp v203, v203, v203 row_ror:2 row_mask:0xf bank_mask:0xf
	v_add_f32_dpp v204, v204, v204 row_ror:2 row_mask:0xf bank_mask:0xf
	v_add_f32_dpp v205, v205, v205 row_ror:2 row_mask:0xf bank_mask:0xf
	v_add_f32_dpp v206, v206, v206 row_ror:2 row_mask:0xf bank_mask:0xf
	v_add_f32_dpp v207, v207, v207 row_ror:2 row_mask:0xf bank_mask:0xf
	v_add_f32_dpp v208, v208, v208 row_ror:2 row_mask:0xf bank_mask:0xf
	v_add_f32_dpp v209, v209, v209 row_ror:2 row_mask:0xf bank_mask:0xf
	v_add_f32_dpp v210, v210, v210 row_ror:2 row_mask:0xf bank_mask:0xf
	v_add_f32_dpp v211, v211, v211 row_ror:2 row_mask:0xf bank_mask:0xf
	v_add_f32_dpp v212, v212, v212 row_ror:2 row_mask:0xf bank_mask:0xf
	v_add_f32_dpp v213, v213, v213 row_ror:2 row_mask:0xf bank_mask:0xf
	v_add_f32_dpp v214, v214, v214 row_ror:2 row_mask:0xf bank_mask:0xf
	v_add_f32_dpp v215, v215, v215 row_ror:2 row_mask:0xf bank_mask:0xf
	v_add_f32_dpp v216, v216, v216 row_ror:2 row_mask:0xf bank_mask:0xf
	v_add_f32_dpp v217, v217, v217 row_ror:2 row_mask:0xf bank_mask:0xf
	v_add_f32_dpp v218, v218, v218 row_ror:2 row_mask:0xf bank_mask:0xf
	v_add_f32_dpp v219, v219, v219 row_ror:2 row_mask:0xf bank_mask:0xf
	v_add_f32_dpp v220, v220, v220 row_ror:2 row_mask:0xf bank_mask:0xf
	v_add_f32_dpp v221, v221, v221 row_ror:2 row_mask:0xf bank_mask:0xf
	v_add_f32_dpp v222, v222, v222 row_ror:2 row_mask:0xf bank_mask:0xf
	v_add_f32_dpp v223, v223, v223 row_ror:2 row_mask:0xf bank_mask:0xf
	v_add_f32_dpp v224, v224, v224 row_ror:2 row_mask:0xf bank_mask:0xf
	v_add_f32_dpp v225, v225, v225 row_ror:2 row_mask:0xf bank_mask:0xf
	s_nop 1
	v_add_f32_dpp v194, v194, v194 row_ror:1 row_mask:0xf bank_mask:0xf
	v_add_f32_dpp v195, v195, v195 row_ror:1 row_mask:0xf bank_mask:0xf
	v_add_f32_dpp v196, v196, v196 row_ror:1 row_mask:0xf bank_mask:0xf
	v_add_f32_dpp v197, v197, v197 row_ror:1 row_mask:0xf bank_mask:0xf
	v_add_f32_dpp v198, v198, v198 row_ror:1 row_mask:0xf bank_mask:0xf
	v_add_f32_dpp v199, v199, v199 row_ror:1 row_mask:0xf bank_mask:0xf
	v_add_f32_dpp v200, v200, v200 row_ror:1 row_mask:0xf bank_mask:0xf
	v_add_f32_dpp v201, v201, v201 row_ror:1 row_mask:0xf bank_mask:0xf
	v_add_f32_dpp v202, v202, v202 row_ror:1 row_mask:0xf bank_mask:0xf
	v_add_f32_dpp v203, v203, v203 row_ror:1 row_mask:0xf bank_mask:0xf
	v_add_f32_dpp v204, v204, v204 row_ror:1 row_mask:0xf bank_mask:0xf
	v_add_f32_dpp v205, v205, v205 row_ror:1 row_mask:0xf bank_mask:0xf
	v_add_f32_dpp v206, v206, v206 row_ror:1 row_mask:0xf bank_mask:0xf
	v_add_f32_dpp v207, v207, v207 row_ror:1 row_mask:0xf bank_mask:0xf
	v_add_f32_dpp v208, v208, v208 row_ror:1 row_mask:0xf bank_mask:0xf
	v_add_f32_dpp v209, v209, v209 row_ror:1 row_mask:0xf bank_mask:0xf
	v_add_f32_dpp v210, v210, v210 row_ror:1 row_mask:0xf bank_mask:0xf
	v_add_f32_dpp v211, v211, v211 row_ror:1 row_mask:0xf bank_mask:0xf
	v_add_f32_dpp v212, v212, v212 row_ror:1 row_mask:0xf bank_mask:0xf
	v_add_f32_dpp v213, v213, v213 row_ror:1 row_mask:0xf bank_mask:0xf
	v_add_f32_dpp v214, v214, v214 row_ror:1 row_mask:0xf bank_mask:0xf
	v_add_f32_dpp v215, v215, v215 row_ror:1 row_mask:0xf bank_mask:0xf
	v_add_f32_dpp v216, v216, v216 row_ror:1 row_mask:0xf bank_mask:0xf
	v_add_f32_dpp v217, v217, v217 row_ror:1 row_mask:0xf bank_mask:0xf
	v_add_f32_dpp v218, v218, v218 row_ror:1 row_mask:0xf bank_mask:0xf
	v_add_f32_dpp v219, v219, v219 row_ror:1 row_mask:0xf bank_mask:0xf
	v_add_f32_dpp v220, v220, v220 row_ror:1 row_mask:0xf bank_mask:0xf
	v_add_f32_dpp v221, v221, v221 row_ror:1 row_mask:0xf bank_mask:0xf
	v_add_f32_dpp v222, v222, v222 row_ror:1 row_mask:0xf bank_mask:0xf
	v_add_f32_dpp v223, v223, v223 row_ror:1 row_mask:0xf bank_mask:0xf
	v_add_f32_dpp v224, v224, v224 row_ror:1 row_mask:0xf bank_mask:0xf
	v_add_f32_dpp v225, v225, v225 row_ror:1 row_mask:0xf bank_mask:0xf
	v_lshlrev_b32_e32 v236, 10, v162
	v_lshl_add_u32 v236, v163, 2, v236
	v_add_u32_e32 v236, 0x20000, v236
	v_cmp_eq_u32_e32 vcc, 0, v160
	s_mov_b64 exec, vcc
	ds_write_b128 v236, v[194:197]
	ds_write_b128 v236, v[198:201] offset:64
	ds_write_b128 v236, v[202:205] offset:128
	ds_write_b128 v236, v[206:209] offset:192
	ds_write_b128 v236, v[210:213] offset:512
	ds_write_b128 v236, v[214:217] offset:576
	ds_write_b128 v236, v[218:221] offset:640
	ds_write_b128 v236, v[222:225] offset:704
	s_mov_b64 exec, -1
	s_waitcnt lgkmcnt(0)
	s_add_u32 s34, s34, s57
	s_addc_u32 s35, s35, 0
	s_lshl_b32 s57, s32, 13
	s_add_u32 s2, s2, s57
	s_addc_u32 s3, s3, 0
	s_cmp_eq_u32 s32, 0
	s_cselect_b32 s0, s0, s36
	s_cselect_b32 s1, s1, s37
	s_add_u32 s94, s94, 0x1000000
	s_addc_u32 s95, s95, 0
	v_readfirstlane_b32 s32, v167
	s_barrier
	s_cmp_lt_u32 s32, 0x100
	s_cbranch_scc0 .Lgo_fz_w1
	v_lshlrev_b32_e32 v238, 2, v167
	v_add_u32_e32 v239, 0x20000, v238
	ds_read_b32 v240, v239
	ds_read_b32 v241, v239 offset:1024
	ds_read_b32 v242, v239 offset:2048
	ds_read_b32 v243, v239 offset:3072
	v_add_u32_e32 v244, s48, v238
	s_waitcnt lgkmcnt(0)
	v_add_f32_e32 v240, v240, v241
	v_add_f32_e32 v240, v240, v242
	v_add_f32_e32 v240, v240, v243
	global_store_dword v244, v240, s[94:95] sc0 sc1
	s_waitcnt vmcnt(0)
.Lgo_fz_w1:
	s_lshr_b32 s57, s32, 6
	s_lshr_b32 vcc_lo, s57, 1
	s_and_b32 vcc_hi, vcc_lo, 1
	s_lshl_b32 vcc_hi, vcc_hi, 4
	s_lshr_b32 vcc_lo, vcc_lo, 1
	s_mul_i32 vcc_lo, vcc_lo, 96
	s_add_u32 vcc_lo, vcc_lo, vcc_hi
	s_add_u32 vcc_lo, vcc_lo, 32
	s_and_b32 vcc_hi, s57, 1
	s_lshl_b32 vcc_hi, vcc_hi, 6
	s_add_u32 vcc_lo, vcc_lo, vcc_hi
	s_lshl_b32 vcc_lo, vcc_lo, 13
	v_add_u32_e32 v183, vcc_lo, v182
	s_lshl_b32 s57, s57, 14
	s_mov_b32 m0, s57
	s_add_u32 s57, s57, 0x400
	global_load_lds_dwordx4 v183, s[0:1]
	v_add_u32_e32 v183, 0x2000, v183
	s_mov_b32 m0, s57
	s_add_u32 s57, s57, 0x400
	global_load_lds_dwordx4 v183, s[0:1]
	v_add_u32_e32 v183, 0x2000, v183
	s_mov_b32 m0, s57
	s_add_u32 s57, s57, 0x400
	global_load_lds_dwordx4 v183, s[0:1]
	v_add_u32_e32 v183, 0x2000, v183
	s_mov_b32 m0, s57
	s_add_u32 s57, s57, 0x400
	global_load_lds_dwordx4 v183, s[0:1]
	v_add_u32_e32 v183, 0x2000, v183
	s_mov_b32 m0, s57
	s_add_u32 s57, s57, 0x400
	global_load_lds_dwordx4 v183, s[0:1]
	v_add_u32_e32 v183, 0x2000, v183
	s_mov_b32 m0, s57
	s_add_u32 s57, s57, 0x400
	global_load_lds_dwordx4 v183, s[0:1]
	v_add_u32_e32 v183, 0x2000, v183
	s_mov_b32 m0, s57
	s_add_u32 s57, s57, 0x400
	global_load_lds_dwordx4 v183, s[0:1]
	v_add_u32_e32 v183, 0x2000, v183
	s_mov_b32 m0, s57
	s_add_u32 s57, s57, 0x400
	global_load_lds_dwordx4 v183, s[0:1]
	v_add_u32_e32 v183, 0x2000, v183
	s_mov_b32 m0, s57
	s_add_u32 s57, s57, 0x400
	global_load_lds_dwordx4 v183, s[0:1]
	v_add_u32_e32 v183, 0x2000, v183
	s_mov_b32 m0, s57
	s_add_u32 s57, s57, 0x400
	global_load_lds_dwordx4 v183, s[0:1]
	v_add_u32_e32 v183, 0x2000, v183
	s_mov_b32 m0, s57
	s_add_u32 s57, s57, 0x400
	global_load_lds_dwordx4 v183, s[0:1]
	v_add_u32_e32 v183, 0x2000, v183
	s_mov_b32 m0, s57
	s_add_u32 s57, s57, 0x400
	global_load_lds_dwordx4 v183, s[0:1]
	v_add_u32_e32 v183, 0x2000, v183
	s_mov_b32 m0, s57
	s_add_u32 s57, s57, 0x400
	global_load_lds_dwordx4 v183, s[0:1]
	v_add_u32_e32 v183, 0x2000, v183
	s_mov_b32 m0, s57
	s_add_u32 s57, s57, 0x400
	global_load_lds_dwordx4 v183, s[0:1]
	v_add_u32_e32 v183, 0x2000, v183
	s_mov_b32 m0, s57
	s_add_u32 s57, s57, 0x400
	global_load_lds_dwordx4 v183, s[0:1]
	v_add_u32_e32 v183, 0x2000, v183
	s_mov_b32 m0, s57
	s_add_u32 s57, s57, 0x400
	global_load_lds_dwordx4 v183, s[0:1]
	v_add_u32_e32 v183, 0x2000, v183
	global_load_dword v226, v237, s[34:35]
	global_load_dword v230, v237, s[2:3]
	global_load_dword v227, v237, s[34:35] offset:64
	global_load_dword v231, v237, s[2:3] offset:64
	global_load_dword v228, v237, s[34:35] offset:512
	global_load_dword v232, v237, s[2:3] offset:512
	global_load_dword v229, v237, s[34:35] offset:576
	global_load_dword v233, v237, s[2:3] offset:576
	v_mov_b32_e32 v172, v168
	v_mov_b32_e32 v173, v169
	v_mov_b32_e32 v174, v170
	v_mov_b32_e32 v175, v171
	global_load_dword v128, v172, s[0:1]
	global_load_dword v129, v173, s[0:1]
	global_load_dword v130, v174, s[0:1]
	global_load_dword v131, v175, s[0:1]
	global_load_dword v132, v172, s[0:1] offset:64
	global_load_dword v133, v173, s[0:1] offset:64
	global_load_dword v134, v174, s[0:1] offset:64
	global_load_dword v135, v175, s[0:1] offset:64
	global_load_dword v136, v172, s[0:1] offset:512
	global_load_dword v137, v173, s[0:1] offset:512
	global_load_dword v138, v174, s[0:1] offset:512
	global_load_dword v139, v175, s[0:1] offset:512
	global_load_dword v140, v172, s[0:1] offset:576
	global_load_dword v141, v173, s[0:1] offset:576
	global_load_dword v142, v174, s[0:1] offset:576
	global_load_dword v143, v175, s[0:1] offset:576
	v_add_u32_e32 v176, 0x20000, v168
	v_add_u32_e32 v177, 0x20000, v169
	v_add_u32_e32 v178, 0x20000, v170
	v_add_u32_e32 v179, 0x20000, v171
	global_load_dword v144, v176, s[0:1]
	global_load_dword v145, v177, s[0:1]
	global_load_dword v146, v178, s[0:1]
	global_load_dword v147, v179, s[0:1]
	global_load_dword v148, v176, s[0:1] offset:64
	global_load_dword v149, v177, s[0:1] offset:64
	global_load_dword v150, v178, s[0:1] offset:64
	global_load_dword v151, v179, s[0:1] offset:64
	global_load_dword v152, v176, s[0:1] offset:512
	global_load_dword v153, v177, s[0:1] offset:512
	global_load_dword v154, v178, s[0:1] offset:512
	global_load_dword v155, v179, s[0:1] offset:512
	global_load_dword v156, v176, s[0:1] offset:576
	global_load_dword v157, v177, s[0:1] offset:576
	global_load_dword v158, v178, s[0:1] offset:576
	global_load_dword v159, v179, s[0:1] offset:576
	s_barrier
	s_cmp_lt_u32 s32, 64
	s_cbranch_scc0 .Lgo_fz_w2
	v_mov_b32_e32 v245, v234
	v_mov_b32_e32 v246, 1
	s_mov_b64 exec, 1
	global_atomic_add v245, v246, s[98:99]
	s_mov_b32 s57, 0

.Lgo_fz_w3:
	s_waitcnt vmcnt(40)
	s_barrier
	v_lshlrev_b32_e32 v236, 2, v163
	v_add_u32_e32 v236, 0x20000, v236
	ds_read_b128 v[194:197], v236
	ds_read_b128 v[198:201], v236 offset:64
	ds_read_b128 v[202:205], v236 offset:128
	ds_read_b128 v[206:209], v236 offset:192
	ds_read_b128 v[210:213], v236 offset:512
	ds_read_b128 v[214:217], v236 offset:576
	ds_read_b128 v[218:221], v236 offset:640
	ds_read_b128 v[222:225], v236 offset:704
	s_waitcnt lgkmcnt(0)
	v_add_u32_e32 v162, 0x10000, v161
	s_waitcnt vmcnt(16)
	ds_read_b32 v238, v161 offset:0
	ds_read_b32 v239, v161 offset:1024
	ds_read_b32 v240, v161 offset:2048
	ds_read_b32 v241, v161 offset:3072
	ds_read_b32 v242, v161 offset:64
	ds_read_b32 v243, v161 offset:1088
	ds_read_b32 v244, v161 offset:2112
	ds_read_b32 v245, v161 offset:3136
	ds_read_b32 v246, v161 offset:512
	ds_read_b32 v247, v161 offset:1536
	ds_read_b32 v248, v161 offset:2560
	ds_read_b32 v249, v161 offset:3584
	ds_read_b32 v250, v161 offset:576
	ds_read_b32 v251, v161 offset:1600
	ds_read_b32 v252, v161 offset:2624
	ds_read_b32 v253, v161 offset:3648
	v_mul_f32_e32 v124, v124, v226
	v_mul_f32_e32 v124, v124, v194
	v_fma_f32 v124, v124, v230, v128
	v_mul_f32_e32 v125, v125, v226
	v_mul_f32_e32 v125, v125, v195
	v_fma_f32 v125, v125, v230, v129
	v_mul_f32_e32 v126, v126, v226
	v_mul_f32_e32 v126, v126, v196
	v_fma_f32 v126, v126, v230, v130
	v_mul_f32_e32 v127, v127, v226
	v_mul_f32_e32 v127, v127, v197
	v_fma_f32 v127, v127, v230, v131
	v_mul_f32_e32 v120, v120, v227
	v_mul_f32_e32 v120, v120, v194
	v_fma_f32 v120, v120, v231, v132
	v_mul_f32_e32 v121, v121, v227
	v_mul_f32_e32 v121, v121, v195
	v_fma_f32 v121, v121, v231, v133
	v_mul_f32_e32 v122, v122, v227
	v_mul_f32_e32 v122, v122, v196
	v_fma_f32 v122, v122, v231, v134
	v_mul_f32_e32 v123, v123, v227
	v_mul_f32_e32 v123, v123, v197
	v_fma_f32 v123, v123, v231, v135
	v_mul_f32_e32 v100, v100, v228
	v_mul_f32_e32 v100, v100, v194
	v_fma_f32 v100, v100, v232, v136
	v_mul_f32_e32 v101, v101, v228
	v_mul_f32_e32 v101, v101, v195
	v_fma_f32 v101, v101, v232, v137
	v_mul_f32_e32 v102, v102, v228
	v_mul_f32_e32 v102, v102, v196
	v_fma_f32 v102, v102, v232, v138
	v_mul_f32_e32 v103, v103, v228
	v_mul_f32_e32 v103, v103, v197
	v_fma_f32 v103, v103, v232, v139
	v_mul_f32_e32 v96, v96, v229
	v_mul_f32_e32 v96, v96, v194
	v_fma_f32 v96, v96, v233, v140
	v_mul_f32_e32 v97, v97, v229
	v_mul_f32_e32 v97, v97, v195
	v_fma_f32 v97, v97, v233, v141
	v_mul_f32_e32 v98, v98, v229
	v_mul_f32_e32 v98, v98, v196
	v_fma_f32 v98, v98, v233, v142
	v_mul_f32_e32 v99, v99, v229
	v_mul_f32_e32 v99, v99, v197
	v_fma_f32 v99, v99, v233, v143
	global_store_dword v172, v124, s[36:37]
	global_store_dword v173, v125, s[36:37]
	global_store_dword v174, v126, s[36:37]
	global_store_dword v175, v127, s[36:37]
	global_store_dword v172, v120, s[36:37] offset:64
	global_store_dword v173, v121, s[36:37] offset:64
	global_store_dword v174, v122, s[36:37] offset:64
	global_store_dword v175, v123, s[36:37] offset:64
	global_store_dword v172, v100, s[36:37] offset:512
	global_store_dword v173, v101, s[36:37] offset:512
	global_store_dword v174, v102, s[36:37] offset:512
	global_store_dword v175, v103, s[36:37] offset:512
	global_store_dword v172, v96, s[36:37] offset:576
	global_store_dword v173, v97, s[36:37] offset:576
	global_store_dword v174, v98, s[36:37] offset:576
	global_store_dword v175, v99, s[36:37] offset:576
	v_add_u32_e32 v172, 0x140000, v168
	v_add_u32_e32 v173, 0x140000, v169
	v_add_u32_e32 v174, 0x140000, v170
	v_add_u32_e32 v175, 0x140000, v171
	global_load_dword v128, v172, s[0:1]
	global_load_dword v129, v173, s[0:1]
	global_load_dword v130, v174, s[0:1]
	global_load_dword v131, v175, s[0:1]
	global_load_dword v132, v172, s[0:1] offset:64
	global_load_dword v133, v173, s[0:1] offset:64
	global_load_dword v134, v174, s[0:1] offset:64
	global_load_dword v135, v175, s[0:1] offset:64
	global_load_dword v136, v172, s[0:1] offset:512
	global_load_dword v137, v173, s[0:1] offset:512
	global_load_dword v138, v174, s[0:1] offset:512
	global_load_dword v139, v175, s[0:1] offset:512
	global_load_dword v140, v172, s[0:1] offset:576
	global_load_dword v141, v173, s[0:1] offset:576
	global_load_dword v142, v174, s[0:1] offset:576
	global_load_dword v143, v175, s[0:1] offset:576
	s_waitcnt vmcnt(32)
	v_mul_f32_e32 v116, v116, v226
	v_mul_f32_e32 v116, v116, v198
	v_fma_f32 v116, v116, v230, v144
	v_mul_f32_e32 v117, v117, v226
	v_mul_f32_e32 v117, v117, v199
	v_fma_f32 v117, v117, v230, v145
	v_mul_f32_e32 v118, v118, v226
	v_mul_f32_e32 v118, v118, v200
	v_fma_f32 v118, v118, v230, v146
	v_mul_f32_e32 v119, v119, v226
	v_mul_f32_e32 v119, v119, v201
	v_fma_f32 v119, v119, v230, v147
	v_mul_f32_e32 v112, v112, v227
	v_mul_f32_e32 v112, v112, v198
	v_fma_f32 v112, v112, v231, v148
	v_mul_f32_e32 v113, v113, v227
	v_mul_f32_e32 v113, v113, v199
	v_fma_f32 v113, v113, v231, v149
	v_mul_f32_e32 v114, v114, v227
	v_mul_f32_e32 v114, v114, v200
	v_fma_f32 v114, v114, v231, v150
	v_mul_f32_e32 v115, v115, v227
	v_mul_f32_e32 v115, v115, v201
	v_fma_f32 v115, v115, v231, v151
	v_mul_f32_e32 v92, v92, v228
	v_mul_f32_e32 v92, v92, v198
	v_fma_f32 v92, v92, v232, v152
	v_mul_f32_e32 v93, v93, v228
	v_mul_f32_e32 v93, v93, v199
	v_fma_f32 v93, v93, v232, v153
	v_mul_f32_e32 v94, v94, v228
	v_mul_f32_e32 v94, v94, v200
	v_fma_f32 v94, v94, v232, v154
	v_mul_f32_e32 v95, v95, v228
	v_mul_f32_e32 v95, v95, v201
	v_fma_f32 v95, v95, v232, v155
	v_mul_f32_e32 v88, v88, v229
	v_mul_f32_e32 v88, v88, v198
	v_fma_f32 v88, v88, v233, v156
	v_mul_f32_e32 v89, v89, v229
	v_mul_f32_e32 v89, v89, v199
	v_fma_f32 v89, v89, v233, v157
	v_mul_f32_e32 v90, v90, v229
	v_mul_f32_e32 v90, v90, v200
	v_fma_f32 v90, v90, v233, v158
	v_mul_f32_e32 v91, v91, v229
	v_mul_f32_e32 v91, v91, v201
	v_fma_f32 v91, v91, v233, v159
	global_store_dword v176, v116, s[36:37]
	global_store_dword v177, v117, s[36:37]
	global_store_dword v178, v118, s[36:37]
	global_store_dword v179, v119, s[36:37]
	global_store_dword v176, v112, s[36:37] offset:64
	global_store_dword v177, v113, s[36:37] offset:64
	global_store_dword v178, v114, s[36:37] offset:64
	global_store_dword v179, v115, s[36:37] offset:64
	global_store_dword v176, v92, s[36:37] offset:512
	global_store_dword v177, v93, s[36:37] offset:512
	global_store_dword v178, v94, s[36:37] offset:512
	global_store_dword v179, v95, s[36:37] offset:512
	global_store_dword v176, v88, s[36:37] offset:576
	global_store_dword v177, v89, s[36:37] offset:576
	global_store_dword v178, v90, s[36:37] offset:576
	global_store_dword v179, v91, s[36:37] offset:576
	v_add_u32_e32 v176, 0x160000, v168
	v_add_u32_e32 v177, 0x160000, v169
	v_add_u32_e32 v178, 0x160000, v170
	v_add_u32_e32 v179, 0x160000, v171
	global_load_dword v144, v176, s[0:1]
	global_load_dword v145, v177, s[0:1]
	global_load_dword v146, v178, s[0:1]
	global_load_dword v147, v179, s[0:1]
	global_load_dword v148, v176, s[0:1] offset:64
	global_load_dword v149, v177, s[0:1] offset:64
	global_load_dword v150, v178, s[0:1] offset:64
	global_load_dword v151, v179, s[0:1] offset:64
	global_load_dword v152, v176, s[0:1] offset:512
	global_load_dword v153, v177, s[0:1] offset:512
	global_load_dword v154, v178, s[0:1] offset:512
	global_load_dword v155, v179, s[0:1] offset:512
	global_load_dword v156, v176, s[0:1] offset:576
	global_load_dword v157, v177, s[0:1] offset:576
	global_load_dword v158, v178, s[0:1] offset:576
	global_load_dword v159, v179, s[0:1] offset:576
	s_waitcnt lgkmcnt(0)
	v_mul_f32_e32 v108, v108, v226
	v_mul_f32_e32 v108, v108, v202
	v_fma_f32 v108, v108, v230, v238
	v_mul_f32_e32 v109, v109, v226
	v_mul_f32_e32 v109, v109, v203
	v_fma_f32 v109, v109, v230, v239
	v_mul_f32_e32 v110, v110, v226
	v_mul_f32_e32 v110, v110, v204
	v_fma_f32 v110, v110, v230, v240
	v_mul_f32_e32 v111, v111, v226
	v_mul_f32_e32 v111, v111, v205
	v_fma_f32 v111, v111, v230, v241
	v_mul_f32_e32 v104, v104, v227
	v_mul_f32_e32 v104, v104, v202
	v_fma_f32 v104, v104, v231, v242
	v_mul_f32_e32 v105, v105, v227
	v_mul_f32_e32 v105, v105, v203
	v_fma_f32 v105, v105, v231, v243
	v_mul_f32_e32 v106, v106, v227
	v_mul_f32_e32 v106, v106, v204
	v_fma_f32 v106, v106, v231, v244
	v_mul_f32_e32 v107, v107, v227
	v_mul_f32_e32 v107, v107, v205
	v_fma_f32 v107, v107, v231, v245
	v_mul_f32_e32 v80, v80, v228
	v_mul_f32_e32 v80, v80, v202
	v_fma_f32 v80, v80, v232, v246
	v_mul_f32_e32 v81, v81, v228
	v_mul_f32_e32 v81, v81, v203
	v_fma_f32 v81, v81, v232, v247
	v_mul_f32_e32 v82, v82, v228
	v_mul_f32_e32 v82, v82, v204
	v_fma_f32 v82, v82, v232, v248
	v_mul_f32_e32 v83, v83, v228
	v_mul_f32_e32 v83, v83, v205
	v_fma_f32 v83, v83, v232, v249
	v_mul_f32_e32 v72, v72, v229
	v_mul_f32_e32 v72, v72, v202
	v_fma_f32 v72, v72, v233, v250
	v_mul_f32_e32 v73, v73, v229
	v_mul_f32_e32 v73, v73, v203
	v_fma_f32 v73, v73, v233, v251
	v_mul_f32_e32 v74, v74, v229
	v_mul_f32_e32 v74, v74, v204
	v_fma_f32 v74, v74, v233, v252
	v_mul_f32_e32 v75, v75, v229
	v_mul_f32_e32 v75, v75, v205
	v_fma_f32 v75, v75, v233, v253
	v_add_u32_e32 v172, 0x40000, v168
	v_add_u32_e32 v173, 0x40000, v169
	v_add_u32_e32 v174, 0x40000, v170
	v_add_u32_e32 v175, 0x40000, v171
	global_store_dword v172, v108, s[36:37]
	global_store_dword v173, v109, s[36:37]
	global_store_dword v174, v110, s[36:37]
	global_store_dword v175, v111, s[36:37]
	global_store_dword v172, v104, s[36:37] offset:64
	global_store_dword v173, v105, s[36:37] offset:64
	global_store_dword v174, v106, s[36:37] offset:64
	global_store_dword v175, v107, s[36:37] offset:64
	global_store_dword v172, v80, s[36:37] offset:512
	global_store_dword v173, v81, s[36:37] offset:512
	global_store_dword v174, v82, s[36:37] offset:512
	global_store_dword v175, v83, s[36:37] offset:512
	global_store_dword v172, v72, s[36:37] offset:576
	global_store_dword v173, v73, s[36:37] offset:576
	global_store_dword v174, v74, s[36:37] offset:576
	global_store_dword v175, v75, s[36:37] offset:576
	ds_read_b32 v238, v161 offset:32768
	ds_read_b32 v239, v161 offset:33792
	ds_read_b32 v240, v161 offset:34816
	ds_read_b32 v241, v161 offset:35840
	ds_read_b32 v242, v161 offset:32832
	ds_read_b32 v243, v161 offset:33856
	ds_read_b32 v244, v161 offset:34880
	ds_read_b32 v245, v161 offset:35904
	ds_read_b32 v246, v161 offset:33280
	ds_read_b32 v247, v161 offset:34304
	ds_read_b32 v248, v161 offset:35328
	ds_read_b32 v249, v161 offset:36352
	ds_read_b32 v250, v161 offset:33344
	ds_read_b32 v251, v161 offset:34368
	ds_read_b32 v252, v161 offset:35392
	ds_read_b32 v253, v161 offset:36416
	s_waitcnt lgkmcnt(0)
	v_mul_f32_e32 v84, v84, v226
	v_mul_f32_e32 v84, v84, v206
	v_fma_f32 v84, v84, v230, v238
	v_mul_f32_e32 v85, v85, v226
	v_mul_f32_e32 v85, v85, v207
	v_fma_f32 v85, v85, v230, v239
	v_mul_f32_e32 v86, v86, v226
	v_mul_f32_e32 v86, v86, v208
	v_fma_f32 v86, v86, v230, v240
	v_mul_f32_e32 v87, v87, v226
	v_mul_f32_e32 v87, v87, v209
	v_fma_f32 v87, v87, v230, v241
	v_mul_f32_e32 v76, v76, v227
	v_mul_f32_e32 v76, v76, v206
	v_fma_f32 v76, v76, v231, v242
	v_mul_f32_e32 v77, v77, v227
	v_mul_f32_e32 v77, v77, v207
	v_fma_f32 v77, v77, v231, v243
	v_mul_f32_e32 v78, v78, v227
	v_mul_f32_e32 v78, v78, v208
	v_fma_f32 v78, v78, v231, v244
	v_mul_f32_e32 v79, v79, v227
	v_mul_f32_e32 v79, v79, v209
	v_fma_f32 v79, v79, v231, v245
	v_mul_f32_e32 v68, v68, v228
	v_mul_f32_e32 v68, v68, v206
	v_fma_f32 v68, v68, v232, v246
	v_mul_f32_e32 v69, v69, v228
	v_mul_f32_e32 v69, v69, v207
	v_fma_f32 v69, v69, v232, v247
	v_mul_f32_e32 v70, v70, v228
	v_mul_f32_e32 v70, v70, v208
	v_fma_f32 v70, v70, v232, v248
	v_mul_f32_e32 v71, v71, v228
	v_mul_f32_e32 v71, v71, v209
	v_fma_f32 v71, v71, v232, v249
	v_mul_f32_e32 v64, v64, v229
	v_mul_f32_e32 v64, v64, v206
	v_fma_f32 v64, v64, v233, v250
	v_mul_f32_e32 v65, v65, v229
	v_mul_f32_e32 v65, v65, v207
	v_fma_f32 v65, v65, v233, v251
	v_mul_f32_e32 v66, v66, v229
	v_mul_f32_e32 v66, v66, v208
	v_fma_f32 v66, v66, v233, v252
	v_mul_f32_e32 v67, v67, v229
	v_mul_f32_e32 v67, v67, v209
	v_fma_f32 v67, v67, v233, v253
	v_add_u32_e32 v176, 0x60000, v168
	v_add_u32_e32 v177, 0x60000, v169
	v_add_u32_e32 v178, 0x60000, v170
	v_add_u32_e32 v179, 0x60000, v171
	global_store_dword v176, v84, s[36:37]
	global_store_dword v177, v85, s[36:37]
	global_store_dword v178, v86, s[36:37]
	global_store_dword v179, v87, s[36:37]
	global_store_dword v176, v76, s[36:37] offset:64
	global_store_dword v177, v77, s[36:37] offset:64
	global_store_dword v178, v78, s[36:37] offset:64
	global_store_dword v179, v79, s[36:37] offset:64
	global_store_dword v176, v68, s[36:37] offset:512
	global_store_dword v177, v69, s[36:37] offset:512
	global_store_dword v178, v70, s[36:37] offset:512
	global_store_dword v179, v71, s[36:37] offset:512
	global_store_dword v176, v64, s[36:37] offset:576
	global_store_dword v177, v65, s[36:37] offset:576
	global_store_dword v178, v66, s[36:37] offset:576
	global_store_dword v179, v67, s[36:37] offset:576
	ds_read_b32 v238, v162 offset:0
	ds_read_b32 v239, v162 offset:1024
	ds_read_b32 v240, v162 offset:2048
	ds_read_b32 v241, v162 offset:3072
	ds_read_b32 v242, v162 offset:64
	ds_read_b32 v243, v162 offset:1088
	ds_read_b32 v244, v162 offset:2112
	ds_read_b32 v245, v162 offset:3136
	ds_read_b32 v246, v162 offset:512
	ds_read_b32 v247, v162 offset:1536
	ds_read_b32 v248, v162 offset:2560
	ds_read_b32 v249, v162 offset:3584
	ds_read_b32 v250, v162 offset:576
	ds_read_b32 v251, v162 offset:1600
	ds_read_b32 v252, v162 offset:2624
	ds_read_b32 v253, v162 offset:3648
	s_waitcnt lgkmcnt(0)
	v_mul_f32_e32 v60, v60, v226
	v_mul_f32_e32 v60, v60, v210
	v_fma_f32 v60, v60, v230, v238
	v_mul_f32_e32 v61, v61, v226
	v_mul_f32_e32 v61, v61, v211
	v_fma_f32 v61, v61, v230, v239
	v_mul_f32_e32 v62, v62, v226
	v_mul_f32_e32 v62, v62, v212
	v_fma_f32 v62, v62, v230, v240
	v_mul_f32_e32 v63, v63, v226
	v_mul_f32_e32 v63, v63, v213
	v_fma_f32 v63, v63, v230, v241
	v_mul_f32_e32 v56, v56, v227
	v_mul_f32_e32 v56, v56, v210
	v_fma_f32 v56, v56, v231, v242
	v_mul_f32_e32 v57, v57, v227
	v_mul_f32_e32 v57, v57, v211
	v_fma_f32 v57, v57, v231, v243
	v_mul_f32_e32 v58, v58, v227
	v_mul_f32_e32 v58, v58, v212
	v_fma_f32 v58, v58, v231, v244
	v_mul_f32_e32 v59, v59, v227
	v_mul_f32_e32 v59, v59, v213
	v_fma_f32 v59, v59, v231, v245
	v_mul_f32_e32 v32, v32, v228
	v_mul_f32_e32 v32, v32, v210
	v_fma_f32 v32, v32, v232, v246
	v_mul_f32_e32 v33, v33, v228
	v_mul_f32_e32 v33, v33, v211
	v_fma_f32 v33, v33, v232, v247
	v_mul_f32_e32 v34, v34, v228
	v_mul_f32_e32 v34, v34, v212
	v_fma_f32 v34, v34, v232, v248
	v_mul_f32_e32 v35, v35, v228
	v_mul_f32_e32 v35, v35, v213
	v_fma_f32 v35, v35, v232, v249
	v_mul_f32_e32 v24, v24, v229
	v_mul_f32_e32 v24, v24, v210
	v_fma_f32 v24, v24, v233, v250
	v_mul_f32_e32 v25, v25, v229
	v_mul_f32_e32 v25, v25, v211
	v_fma_f32 v25, v25, v233, v251
	v_mul_f32_e32 v26, v26, v229
	v_mul_f32_e32 v26, v26, v212
	v_fma_f32 v26, v26, v233, v252
	v_mul_f32_e32 v27, v27, v229
	v_mul_f32_e32 v27, v27, v213
	v_fma_f32 v27, v27, v233, v253
	v_add_u32_e32 v172, 0x100000, v168
	v_add_u32_e32 v173, 0x100000, v169
	v_add_u32_e32 v174, 0x100000, v170
	v_add_u32_e32 v175, 0x100000, v171
	global_store_dword v172, v60, s[36:37]
	global_store_dword v173, v61, s[36:37]
	global_store_dword v174, v62, s[36:37]
	global_store_dword v175, v63, s[36:37]
	global_store_dword v172, v56, s[36:37] offset:64
	global_store_dword v173, v57, s[36:37] offset:64
	global_store_dword v174, v58, s[36:37] offset:64
	global_store_dword v175, v59, s[36:37] offset:64
	global_store_dword v172, v32, s[36:37] offset:512
	global_store_dword v173, v33, s[36:37] offset:512
	global_store_dword v174, v34, s[36:37] offset:512
	global_store_dword v175, v35, s[36:37] offset:512
	global_store_dword v172, v24, s[36:37] offset:576
	global_store_dword v173, v25, s[36:37] offset:576
	global_store_dword v174, v26, s[36:37] offset:576
	global_store_dword v175, v27, s[36:37] offset:576
	ds_read_b32 v238, v162 offset:32768
	ds_read_b32 v239, v162 offset:33792
	ds_read_b32 v240, v162 offset:34816
	ds_read_b32 v241, v162 offset:35840
	ds_read_b32 v242, v162 offset:32832
	ds_read_b32 v243, v162 offset:33856
	ds_read_b32 v244, v162 offset:34880
	ds_read_b32 v245, v162 offset:35904
	ds_read_b32 v246, v162 offset:33280
	ds_read_b32 v247, v162 offset:34304
	ds_read_b32 v248, v162 offset:35328
	ds_read_b32 v249, v162 offset:36352
	ds_read_b32 v250, v162 offset:33344
	ds_read_b32 v251, v162 offset:34368
	ds_read_b32 v252, v162 offset:35392
	ds_read_b32 v253, v162 offset:36416
	s_waitcnt lgkmcnt(0)
	v_mul_f32_e32 v52, v52, v226
	v_mul_f32_e32 v52, v52, v214
	v_fma_f32 v52, v52, v230, v238
	v_mul_f32_e32 v53, v53, v226
	v_mul_f32_e32 v53, v53, v215
	v_fma_f32 v53, v53, v230, v239
	v_mul_f32_e32 v54, v54, v226
	v_mul_f32_e32 v54, v54, v216
	v_fma_f32 v54, v54, v230, v240
	v_mul_f32_e32 v55, v55, v226
	v_mul_f32_e32 v55, v55, v217
	v_fma_f32 v55, v55, v230, v241
	v_mul_f32_e32 v48, v48, v227
	v_mul_f32_e32 v48, v48, v214
	v_fma_f32 v48, v48, v231, v242
	v_mul_f32_e32 v49, v49, v227
	v_mul_f32_e32 v49, v49, v215
	v_fma_f32 v49, v49, v231, v243
	v_mul_f32_e32 v50, v50, v227
	v_mul_f32_e32 v50, v50, v216
	v_fma_f32 v50, v50, v231, v244
	v_mul_f32_e32 v51, v51, v227
	v_mul_f32_e32 v51, v51, v217
	v_fma_f32 v51, v51, v231, v245
	v_mul_f32_e32 v20, v20, v228
	v_mul_f32_e32 v20, v20, v214
	v_fma_f32 v20, v20, v232, v246
	v_mul_f32_e32 v21, v21, v228
	v_mul_f32_e32 v21, v21, v215
	v_fma_f32 v21, v21, v232, v247
	v_mul_f32_e32 v22, v22, v228
	v_mul_f32_e32 v22, v22, v216
	v_fma_f32 v22, v22, v232, v248
	v_mul_f32_e32 v23, v23, v228
	v_mul_f32_e32 v23, v23, v217
	v_fma_f32 v23, v23, v232, v249
	v_mul_f32_e32 v16, v16, v229
	v_mul_f32_e32 v16, v16, v214
	v_fma_f32 v16, v16, v233, v250
	v_mul_f32_e32 v17, v17, v229
	v_mul_f32_e32 v17, v17, v215
	v_fma_f32 v17, v17, v233, v251
	v_mul_f32_e32 v18, v18, v229
	v_mul_f32_e32 v18, v18, v216
	v_fma_f32 v18, v18, v233, v252
	v_mul_f32_e32 v19, v19, v229
	v_mul_f32_e32 v19, v19, v217
	v_fma_f32 v19, v19, v233, v253
	v_add_u32_e32 v176, 0x120000, v168
	v_add_u32_e32 v177, 0x120000, v169
	v_add_u32_e32 v178, 0x120000, v170
	v_add_u32_e32 v179, 0x120000, v171
	global_store_dword v176, v52, s[36:37]
	global_store_dword v177, v53, s[36:37]
	global_store_dword v178, v54, s[36:37]
	global_store_dword v179, v55, s[36:37]
	global_store_dword v176, v48, s[36:37] offset:64
	global_store_dword v177, v49, s[36:37] offset:64
	global_store_dword v178, v50, s[36:37] offset:64
	global_store_dword v179, v51, s[36:37] offset:64
	global_store_dword v176, v20, s[36:37] offset:512
	global_store_dword v177, v21, s[36:37] offset:512
	global_store_dword v178, v22, s[36:37] offset:512
	global_store_dword v179, v23, s[36:37] offset:512
	global_store_dword v176, v16, s[36:37] offset:576
	global_store_dword v177, v17, s[36:37] offset:576
	global_store_dword v178, v18, s[36:37] offset:576
	global_store_dword v179, v19, s[36:37] offset:576
	s_waitcnt vmcnt(63)
	v_mul_f32_e32 v44, v44, v226
	v_mul_f32_e32 v44, v44, v218
	v_fma_f32 v44, v44, v230, v128
	v_mul_f32_e32 v45, v45, v226
	v_mul_f32_e32 v45, v45, v219
	v_fma_f32 v45, v45, v230, v129
	v_mul_f32_e32 v46, v46, v226
	v_mul_f32_e32 v46, v46, v220
	v_fma_f32 v46, v46, v230, v130
	v_mul_f32_e32 v47, v47, v226
	v_mul_f32_e32 v47, v47, v221
	v_fma_f32 v47, v47, v230, v131
	v_mul_f32_e32 v40, v40, v227
	v_mul_f32_e32 v40, v40, v218
	v_fma_f32 v40, v40, v231, v132
	v_mul_f32_e32 v41, v41, v227
	v_mul_f32_e32 v41, v41, v219
	v_fma_f32 v41, v41, v231, v133
	v_mul_f32_e32 v42, v42, v227
	v_mul_f32_e32 v42, v42, v220
	v_fma_f32 v42, v42, v231, v134
	v_mul_f32_e32 v43, v43, v227
	v_mul_f32_e32 v43, v43, v221
	v_fma_f32 v43, v43, v231, v135
	v_mul_f32_e32 v12, v12, v228
	v_mul_f32_e32 v12, v12, v218
	v_fma_f32 v12, v12, v232, v136
	v_mul_f32_e32 v13, v13, v228
	v_mul_f32_e32 v13, v13, v219
	v_fma_f32 v13, v13, v232, v137
	v_mul_f32_e32 v14, v14, v228
	v_mul_f32_e32 v14, v14, v220
	v_fma_f32 v14, v14, v232, v138
	v_mul_f32_e32 v15, v15, v228
	v_mul_f32_e32 v15, v15, v221
	v_fma_f32 v15, v15, v232, v139
	v_mul_f32_e32 v8, v8, v229
	v_mul_f32_e32 v8, v8, v218
	v_fma_f32 v8, v8, v233, v140
	v_mul_f32_e32 v9, v9, v229
	v_mul_f32_e32 v9, v9, v219
	v_fma_f32 v9, v9, v233, v141
	v_mul_f32_e32 v10, v10, v229
	v_mul_f32_e32 v10, v10, v220
	v_fma_f32 v10, v10, v233, v142
	v_mul_f32_e32 v11, v11, v229
	v_mul_f32_e32 v11, v11, v221
	v_fma_f32 v11, v11, v233, v143
	v_add_u32_e32 v172, 0x140000, v168
	v_add_u32_e32 v173, 0x140000, v169
	v_add_u32_e32 v174, 0x140000, v170
	v_add_u32_e32 v175, 0x140000, v171
	global_store_dword v172, v44, s[36:37]
	global_store_dword v173, v45, s[36:37]
	global_store_dword v174, v46, s[36:37]
	global_store_dword v175, v47, s[36:37]
	global_store_dword v172, v40, s[36:37] offset:64
	global_store_dword v173, v41, s[36:37] offset:64
	global_store_dword v174, v42, s[36:37] offset:64
	global_store_dword v175, v43, s[36:37] offset:64
	global_store_dword v172, v12, s[36:37] offset:512
	global_store_dword v173, v13, s[36:37] offset:512
	global_store_dword v174, v14, s[36:37] offset:512
	global_store_dword v175, v15, s[36:37] offset:512
	global_store_dword v172, v8, s[36:37] offset:576
	global_store_dword v173, v9, s[36:37] offset:576
	global_store_dword v174, v10, s[36:37] offset:576
	global_store_dword v175, v11, s[36:37] offset:576
	v_mul_f32_e32 v36, v36, v226
	v_mul_f32_e32 v36, v36, v222
	v_fma_f32 v36, v36, v230, v144
	v_mul_f32_e32 v37, v37, v226
	v_mul_f32_e32 v37, v37, v223
	v_fma_f32 v37, v37, v230, v145
	v_mul_f32_e32 v38, v38, v226
	v_mul_f32_e32 v38, v38, v224
	v_fma_f32 v38, v38, v230, v146
	v_mul_f32_e32 v39, v39, v226
	v_mul_f32_e32 v39, v39, v225
	v_fma_f32 v39, v39, v230, v147
	v_mul_f32_e32 v28, v28, v227
	v_mul_f32_e32 v28, v28, v222
	v_fma_f32 v28, v28, v231, v148
	v_mul_f32_e32 v29, v29, v227
	v_mul_f32_e32 v29, v29, v223
	v_fma_f32 v29, v29, v231, v149
	v_mul_f32_e32 v30, v30, v227
	v_mul_f32_e32 v30, v30, v224
	v_fma_f32 v30, v30, v231, v150
	v_mul_f32_e32 v31, v31, v227
	v_mul_f32_e32 v31, v31, v225
	v_fma_f32 v31, v31, v231, v151
	v_mul_f32_e32 v4, v4, v228
	v_mul_f32_e32 v4, v4, v222
	v_fma_f32 v4, v4, v232, v152
	v_mul_f32_e32 v5, v5, v228
	v_mul_f32_e32 v5, v5, v223
	v_fma_f32 v5, v5, v232, v153
	v_mul_f32_e32 v6, v6, v228
	v_mul_f32_e32 v6, v6, v224
	v_fma_f32 v6, v6, v232, v154
	v_mul_f32_e32 v7, v7, v228
	v_mul_f32_e32 v7, v7, v225
	v_fma_f32 v7, v7, v232, v155
	v_mul_f32_e32 v0, v0, v229
	v_mul_f32_e32 v0, v0, v222
	v_fma_f32 v0, v0, v233, v156
	v_mul_f32_e32 v1, v1, v229
	v_mul_f32_e32 v1, v1, v223
	v_fma_f32 v1, v1, v233, v157
	v_mul_f32_e32 v2, v2, v229
	v_mul_f32_e32 v2, v2, v224
	v_fma_f32 v2, v2, v233, v158
	v_mul_f32_e32 v3, v3, v229
	v_mul_f32_e32 v3, v3, v225
	v_fma_f32 v3, v3, v233, v159
	v_add_u32_e32 v176, 0x160000, v168
	v_add_u32_e32 v177, 0x160000, v169
	v_add_u32_e32 v178, 0x160000, v170
	v_add_u32_e32 v179, 0x160000, v171
	global_store_dword v176, v36, s[36:37]
	global_store_dword v177, v37, s[36:37]
	global_store_dword v178, v38, s[36:37]
	global_store_dword v179, v39, s[36:37]
	global_store_dword v176, v28, s[36:37] offset:64
	global_store_dword v177, v29, s[36:37] offset:64
	global_store_dword v178, v30, s[36:37] offset:64
	global_store_dword v179, v31, s[36:37] offset:64
	global_store_dword v176, v4, s[36:37] offset:512
	global_store_dword v177, v5, s[36:37] offset:512
	global_store_dword v178, v6, s[36:37] offset:512
	global_store_dword v179, v7, s[36:37] offset:512
	global_store_dword v176, v0, s[36:37] offset:576
	global_store_dword v177, v1, s[36:37] offset:576
	global_store_dword v178, v2, s[36:37] offset:576
	global_store_dword v179, v3, s[36:37] offset:576
	v_readlane_b32 s0, v254, 1
	s_add_i32 s44, s44, s0
	s_barrier
	v_readlane_b32 s1, v254, 2
	s_cmp_ge_i32 s44, s46
	s_cbranch_scc1 .LBB0_1172
